# attention softmax: v_max3 tree (8 ops instead of 24), cross-half row max via v_permlane32_swap instead of ds_bpermute, plus rescale threshold
# speedup vs baseline: 1.0193x; 1.0060x over previous
; template <int DQ, int TYPE>
; __device__ __forceinline__ void attn_item(PP p, int layer, int b, int h, int qt, char* lds, const int tid_, unsigned* next_ctr, volatile XLAS unsigned* slot) {
;     ...
;         if (!skip) {
;             const bf16_t* Ks = (const bf16_t*)(lds + buf * STAGE); const bf16_t* Vt = (const bf16_t*)(lds + buf * STAGE + KBYTES);
;             f32x16 sacc;
; #pragma unroll
;             for (int i = 0; i < 16; ++i) sacc[i] = 0.f;
;             const bf16_t* kb_ = Ks + (32 * kh + r) * KLD + 8 * hh;
;             bf16x8 kf[2][GK];
; #pragma unroll
;             for (int i = 0; i < GK; ++i) kf[0][i] = *(const bf16x8*)(kb_ + 16 * i);
; #pragma unroll
;             for (int g = 0; g < NG; ++g) {
;                 if (g + 1 < NG) {
; #pragma unroll
;                     for (int i = 0; i < GK; ++i) kf[(g + 1) & 1][i] = *(const bf16x8*)(kb_ + 16 * ((g + 1) * GK + i));
;                 }
;                 __builtin_amdgcn_sched_barrier(0);
; #pragma unroll
;                 for (int i = 0; i < GK; ++i) sacc = __builtin_amdgcn_mfma_f32_32x32x16_bf16(kf[g & 1][i], qf[g * GK + i], sacc, 0, 0, 0);
;                 __builtin_amdgcn_sched_barrier(0);
;             }
;             const bf16_t* vb0 = Vt + r * VLD + 32 * kh + 4 * hh;
;             u32x2 vf[2][4][2];
; #pragma unroll
;             for (int md = 0; md < 4; ++md) { vf[0][md][0] = *(const u32x2*)(vb0 + md * 32 * VLD); vf[0][md][1] = *(const u32x2*)(vb0 + md * 32 * VLD + 8); }
;             if (mode != 0) {
;                 const bool selbit = (qmask >> (j >> 2)) & 1u;
; #pragma unroll
;                 for (int i = 0; i < 16; ++i) {
;                     const int kpos = kbase_pos + 8 * (i >> 2) + 4 * hh + (i & 3);
;                     const int dd = qpos - kpos;
;                     bool ok;
;                     if (mode == 1) ok = dd >= 0; else if (mode == 2) ok = (dd >= 0 && dd < 128); else ok = selbit;
;                     if (!ok) sacc[i] = -INFINITY;
;                 }
;             }
;             float mx = fmaxf(sacc[0], sacc[1]);
; #pragma unroll
;             for (int i = 2; i < 16; i += 2) mx = fmaxf(mx, fmaxf(sacc[i], sacc[i + 1]));
;             mx *= c;
;             mx = fmaxf(mx, __shfl_xor(mx, 32));
;             const float m_old_ = m_run;
;             const float mnew = fmaxf(m_run, mx);
;             const float alpha = fast_exp2(m_run - mnew);
.LBB0_408:
	s_and_b32 s60, s12, 1
	s_cmp_gt_i32 s59, s57
	s_cselect_b64 s[62:63], -1, 0
	s_add_i32 s61, s59, 31
	s_cmp_le_i32 s61, s58
	s_cselect_b64 s[64:65], -1, 0
	s_or_b64 s[62:63], s[64:65], s[62:63]
	s_and_b64 vcc, exec, s[62:63]
	s_cbranch_vccnz .LBB0_412
	s_mul_i32 s61, s60, 0x8800
	s_add_i32 s61, s61, 16
	v_add3_u32 v0, s61, v163, v167
	ds_read_b128 v[2:5], v0
	ds_read_b128 v[6:9], v0 offset:32
	ds_read_b128 v[10:13], v0 offset:64
	ds_read_b128 v[170:173], v0 offset:96
	ds_read_b128 v[174:177], v0 offset:128
	ds_read_b128 v[190:193], v0 offset:160
	ds_read_b128 v[194:197], v0 offset:192
	ds_read_b128 v[198:201], v0 offset:224
	s_waitcnt vmcnt(7) lgkmcnt(7)
	v_mfma_f32_32x32x16_bf16 v[80:95], v[2:5], v[104:107], 0
	s_waitcnt vmcnt(6) lgkmcnt(6)
	v_mfma_f32_32x32x16_bf16 v[80:95], v[6:9], v[108:111], v[80:95]
	s_waitcnt vmcnt(5) lgkmcnt(5)
	v_mfma_f32_32x32x16_bf16 v[80:95], v[10:13], v[112:115], v[80:95]
	s_waitcnt vmcnt(4) lgkmcnt(4)
	v_mfma_f32_32x32x16_bf16 v[80:95], v[170:173], v[120:123], v[80:95]
	s_waitcnt vmcnt(3) lgkmcnt(3)
	v_mfma_f32_32x32x16_bf16 v[80:95], v[174:177], v[124:127], v[80:95]
	s_lshl_b32 s62, s13, 1
	v_add_u32_e32 v10, 27, v165
	s_add_i32 s62, s62, s61
	v_cmp_gt_u32_e32 vcc, s42, v10
	s_movk_i32 s61, 0xff7f
	v_add_u32_e32 v11, 25, v165
	v_add_u32_e32 v12, 24, v165
	s_waitcnt vmcnt(2) lgkmcnt(2)
	v_mfma_f32_32x32x16_bf16 v[80:95], v[190:193], v[132:135], v[80:95]
	v_add_u32_e32 v13, 19, v165
	v_add_u32_e32 v14, 18, v165
	v_add_u32_e32 v175, 17, v165
	v_add_u32_e32 v176, 16, v165
	v_add_u32_e32 v10, 11, v165
	v_lshlrev_b32_e32 v0, 1, v155
	v_add3_u32 v0, s62, v164, v0
	s_waitcnt vmcnt(1) lgkmcnt(1)
	v_mfma_f32_32x32x16_bf16 v[80:95], v[194:197], v[136:139], v[80:95]
	v_add_u32_e32 v169, 0x4000, v0
	v_add_u32_e32 v15, 0x5000, v0
	ds_read2_b64 v[2:5], v169 offset0:128 offset1:130
	ds_read2_b64 v[6:9], v15 offset0:160 offset1:162
	s_waitcnt vmcnt(0) lgkmcnt(2)
	v_mfma_f32_32x32x16_bf16 v[80:95], v[198:201], v[140:143], v[80:95]
	s_nop 11
	v_cndmask_b32_e32 v170, v225, v80, vcc
	v_cmp_lt_u32_e32 vcc, s61, v166
	s_nop 1
	v_cndmask_b32_e32 v172, v225, v81, vcc
	v_cmp_gt_u32_e32 vcc, s42, v11
	s_nop 1
	v_cndmask_b32_e32 v173, v225, v82, vcc
	v_cmp_gt_u32_e32 vcc, s42, v12
	v_max_f32_e32 v11, v173, v173
	s_nop 0
	v_cndmask_b32_e32 v174, v225, v83, vcc
	v_cmp_gt_u32_e32 vcc, s42, v13
	s_nop 1
	v_cndmask_b32_e32 v171, v225, v84, vcc
	v_cmp_gt_u32_e32 vcc, s42, v14
	v_max_f32_e32 v12, v171, v171
	s_nop 0
	v_cndmask_b32_e32 v85, v225, v85, vcc
	v_cmp_gt_u32_e32 vcc, s42, v175
	s_nop 1
	v_cndmask_b32_e32 v177, v225, v86, vcc
	v_cmp_gt_u32_e32 vcc, s42, v176
	v_max_f32_e32 v13, v177, v177
	s_nop 0
	v_cndmask_b32_e32 v176, v225, v87, vcc
	v_cmp_gt_u32_e32 vcc, s42, v10
	v_add_u32_e32 v10, 10, v165
	s_nop 0
	v_cndmask_b32_e32 v175, v225, v88, vcc
	v_cmp_gt_u32_e32 vcc, s42, v10
	v_add_u32_e32 v10, 9, v165
	s_nop 0
	v_cndmask_b32_e32 v89, v225, v89, vcc
	v_cmp_gt_u32_e32 vcc, s42, v10
	v_add_u32_e32 v10, 8, v165
	s_nop 0
	v_cndmask_b32_e32 v90, v225, v90, vcc
	v_cmp_gt_u32_e32 vcc, s42, v10
	v_add_u32_e32 v10, 3, v165
	s_nop 0
	v_cndmask_b32_e32 v91, v225, v91, vcc
	v_cmp_gt_u32_e32 vcc, s42, v10
	v_add_u32_e32 v10, 2, v165
	s_nop 0
	v_cndmask_b32_e32 v86, v225, v92, vcc
	v_cmp_gt_u32_e32 vcc, s42, v10
	v_add_u32_e32 v10, 1, v165
	v_add_u32_e32 v92, 0x7000, v0
	v_cndmask_b32_e32 v87, v225, v93, vcc
	v_cmp_gt_u32_e32 vcc, s42, v10
	v_max_f32_e32 v10, v174, v174
	v_max_f32_e32 v10, v11, v10
	v_max_f32_e32 v11, v85, v85
	v_max_f32_e32 v11, v12, v11
	v_max_f32_e32 v12, v176, v176
	v_max3_f32 v10, v170, v172, v10
	v_max_f32_e32 v12, v13, v12
	v_max3_f32 v10, v10, v11, v12
	v_max_f32_e32 v11, v89, v89
	v_max_f32_e32 v12, v175, v175
	v_max_f32_e32 v11, v12, v11
	v_max_f32_e32 v12, v91, v91
	v_max_f32_e32 v13, v90, v90
	v_cndmask_b32_e32 v88, v225, v94, vcc
	v_cmp_gt_u32_e32 vcc, s42, v165
	v_max_f32_e32 v12, v13, v12
	v_max3_f32 v10, v10, v11, v12
	v_cndmask_b32_e32 v84, v225, v95, vcc
	v_max_f32_e32 v11, v87, v87
	v_max_f32_e32 v12, v86, v86
	v_max_f32_e32 v11, v12, v11
	v_max_f32_e32 v12, v84, v84
	v_max_f32_e32 v13, v88, v88
	v_max_f32_e32 v12, v13, v12
	v_max3_f32 v10, v10, v11, v12
	v_mul_f32_e32 v14, 0x3e0293ee, v10
	v_add_u32_e32 v93, 0x6000, v0
	ds_read2_b64 v[80:83], v93 offset0:192 offset1:194
	v_mov_b32_e32 v94, v14
	ds_read2_b64 v[10:13], v92 offset0:224 offset1:226
	s_nop 1
	v_permlane32_swap_b32_e32 v94, v14
	v_max_f32_e32 v94, v14, v94
	v_add_f32_e32 v0, 0x41000000, v168
	v_cmp_gt_f32_e32 vcc, v94, v0
	s_nop 1
	v_cndmask_b32_e32 v14, v168, v94, vcc
	v_sub_f32_e32 v0, v168, v14
	v_exp_f32_e32 v0, v0
	s_cbranch_vccz .LBB0_411
	v_pk_mul_f32 v[46:47], v[46:47], v[0:1] op_sel_hi:[1,0]
	v_pk_mul_f32 v[44:45], v[44:45], v[0:1] op_sel_hi:[1,0]
	v_pk_mul_f32 v[42:43], v[42:43], v[0:1] op_sel_hi:[1,0]
	v_pk_mul_f32 v[40:41], v[40:41], v[0:1] op_sel_hi:[1,0]
	v_pk_mul_f32 v[38:39], v[38:39], v[0:1] op_sel_hi:[1,0]
	v_pk_mul_f32 v[36:37], v[36:37], v[0:1] op_sel_hi:[1,0]
	v_pk_mul_f32 v[34:35], v[34:35], v[0:1] op_sel_hi:[1,0]
	v_pk_mul_f32 v[32:33], v[32:33], v[0:1] op_sel_hi:[1,0]
	v_pk_mul_f32 v[30:31], v[30:31], v[0:1] op_sel_hi:[1,0]
	v_pk_mul_f32 v[28:29], v[28:29], v[0:1] op_sel_hi:[1,0]
	v_pk_mul_f32 v[26:27], v[26:27], v[0:1] op_sel_hi:[1,0]
	v_pk_mul_f32 v[24:25], v[24:25], v[0:1] op_sel_hi:[1,0]
	v_pk_mul_f32 v[22:23], v[22:23], v[0:1] op_sel_hi:[1,0]
	v_pk_mul_f32 v[20:21], v[20:21], v[0:1] op_sel_hi:[1,0]
	v_pk_mul_f32 v[18:19], v[18:19], v[0:1] op_sel_hi:[1,0]
	v_pk_mul_f32 v[16:17], v[16:17], v[0:1] op_sel_hi:[1,0]
	v_pk_mul_f32 v[78:79], v[78:79], v[0:1] op_sel_hi:[1,0]
	v_pk_mul_f32 v[76:77], v[76:77], v[0:1] op_sel_hi:[1,0]
	v_pk_mul_f32 v[74:75], v[74:75], v[0:1] op_sel_hi:[1,0]
	v_pk_mul_f32 v[72:73], v[72:73], v[0:1] op_sel_hi:[1,0]
	v_pk_mul_f32 v[70:71], v[70:71], v[0:1] op_sel_hi:[1,0]
	v_pk_mul_f32 v[68:69], v[68:69], v[0:1] op_sel_hi:[1,0]
	v_pk_mul_f32 v[66:67], v[66:67], v[0:1] op_sel_hi:[1,0]
	v_pk_mul_f32 v[64:65], v[64:65], v[0:1] op_sel_hi:[1,0]
	v_pk_mul_f32 v[62:63], v[62:63], v[0:1] op_sel_hi:[1,0]
	v_pk_mul_f32 v[60:61], v[60:61], v[0:1] op_sel_hi:[1,0]
	v_pk_mul_f32 v[58:59], v[58:59], v[0:1] op_sel_hi:[1,0]
	v_pk_mul_f32 v[56:57], v[56:57], v[0:1] op_sel_hi:[1,0]
	v_pk_mul_f32 v[54:55], v[54:55], v[0:1] op_sel_hi:[1,0]
	v_pk_mul_f32 v[52:53], v[52:53], v[0:1] op_sel_hi:[1,0]
	v_pk_mul_f32 v[50:51], v[50:51], v[0:1] op_sel_hi:[1,0]
	v_pk_mul_f32 v[48:49], v[48:49], v[0:1] op_sel_hi:[1,0]
; __device__ __forceinline__ unsigned cvt_pk_bf16(float lo, float hi) { unsigned r; asm volatile("v_cvt_pk_bf16_f32 %0, %1, %2" : "=v"(r) : "v"(lo), "v"(hi)); return r; }
; __device__ __forceinline__ float fast_exp2(float x) { return __builtin_amdgcn_exp2f(x); }
; template <int DQ, int TYPE>
; __device__ __forceinline__ void attn_item(PP p, int layer, int b, int h, int qt, char* lds, const int tid_, unsigned* next_ctr, volatile XLAS unsigned* slot) {
;     ...
;             const float alpha = fast_exp2(m_run - mnew);
;             m_run = mnew;
;             float ls = 0.f;
; #pragma unroll
;             for (int i = 0; i < 16; ++i) { sacc[i] = fast_exp2(__builtin_fmaf(sacc[i], c, -mnew)); ls += sacc[i]; }
;             l_run = l_run * alpha + ls;
;             if (__builtin_amdgcn_ballot_w64(mx > m_old_) != 0) {
; #pragma unroll
;                 for (int md = 0; md < 4; ++md) O[md] *= alpha;
;             }
; #pragma unroll
;             for (int s2 = 0; s2 < 2; ++s2) {
;                 if (s2 == 0) {
; #pragma unroll
;                     for (int md = 0; md < 4; ++md) { vf[1][md][0] = *(const u32x2*)(vb0 + 16 + md * 32 * VLD); vf[1][md][1] = *(const u32x2*)(vb0 + 16 + md * 32 * VLD + 8); }
;                 }
;                 u32x4 pb;
;                 pb.x = cvt_pk_bf16(sacc[8 * s2 + 0], sacc[8 * s2 + 1]); pb.y = cvt_pk_bf16(sacc[8 * s2 + 2], sacc[8 * s2 + 3]);
;                 pb.z = cvt_pk_bf16(sacc[8 * s2 + 4], sacc[8 * s2 + 5]); pb.w = cvt_pk_bf16(sacc[8 * s2 + 6], sacc[8 * s2 + 7]);
;                 const bf16x8 bfrag = __builtin_bit_cast(bf16x8, pb);
;                 __builtin_amdgcn_sched_barrier(0);
; #pragma unroll
;                 for (int md = 0; md < 4; ++md) {
;                     u32x4 av; av.x = vf[s2][md][0].x; av.y = vf[s2][md][0].y; av.z = vf[s2][md][1].x; av.w = vf[s2][md][1].y;
;                     O[md] = __builtin_amdgcn_mfma_f32_32x32x16_bf16(__builtin_bit_cast(bf16x8, av), bfrag, O[md], 0, 0, 0);
;                 }
;                 __builtin_amdgcn_sched_barrier(0);
;             }
.LBB0_411:
	v_fma_f32 v94, v170, s33, -v14
	v_exp_f32_e32 v183, v94
	v_fma_f32 v94, v172, s33, -v14
	v_exp_f32_e32 v172, v94
	v_fma_f32 v94, v173, s33, -v14
	v_exp_f32_e32 v173, v94
	v_fma_f32 v94, v174, s33, -v14
	v_exp_f32_e32 v174, v94
	v_fma_f32 v95, v171, s33, -v14
	v_add_f32_e32 v94, 0, v183
	v_exp_f32_e32 v185, v95
	v_add_f32_e32 v94, v172, v94
	v_fma_f32 v85, v85, s33, -v14
	v_add_f32_e32 v94, v173, v94
	v_exp_f32_e32 v187, v85
	v_fma_f32 v85, v177, s33, -v14
	v_add_f32_e32 v94, v174, v94
	v_exp_f32_e32 v177, v85
	v_fma_f32 v85, v176, s33, -v14
	v_exp_f32_e32 v176, v85
	v_add_f32_e32 v85, v185, v94
	v_fma_f32 v94, v175, s33, -v14
	v_exp_f32_e32 v189, v94
	v_fma_f32 v89, v89, s33, -v14
	v_add_f32_e32 v85, v187, v85
	v_exp_f32_e32 v190, v89
	v_fma_f32 v89, v90, s33, -v14
	v_add_f32_e32 v85, v177, v85
	v_exp_f32_e32 v191, v89
	v_fma_f32 v89, v91, s33, -v14
	v_add_f32_e32 v85, v176, v85
	v_exp_f32_e32 v192, v89
	v_fma_f32 v86, v86, s33, -v14
	v_add_f32_e32 v85, v189, v85
	v_exp_f32_e32 v193, v86
	v_fma_f32 v86, v87, s33, -v14
	v_add_f32_e32 v85, v190, v85
	v_exp_f32_e32 v194, v86
	v_fma_f32 v86, v88, s33, -v14
	v_add_f32_e32 v85, v191, v85
	v_exp_f32_e32 v195, v86
	v_fma_f32 v84, v84, s33, -v14
	v_add_f32_e32 v85, v192, v85
	v_exp_f32_e32 v196, v84
	v_add_f32_e32 v84, v193, v85
	v_add_f32_e32 v84, v194, v84
	v_add_f32_e32 v84, v195, v84
	v_add_f32_e32 v197, v196, v84
	ds_read2_b64 v[84:87], v169 offset0:132 offset1:134
	ds_read2_b64 v[88:91], v15 offset0:164 offset1:166
	ds_read2_b64 v[168:171], v93 offset0:196 offset1:198
	ds_read2_b64 v[92:95], v92 offset0:228 offset1:230
	v_fmac_f32_e32 v197, v158, v0
	v_cvt_pk_bf16_f32 v172, v183, v172
	v_cvt_pk_bf16_f32 v173, v173, v174
	v_cvt_pk_bf16_f32 v174, v185, v187
	v_cvt_pk_bf16_f32 v175, v177, v176
	s_waitcnt lgkmcnt(5)
	s_nop 0
	v_mfma_f32_32x32x16_bf16 v[32:47], v[2:5], v[172:175], v[32:47]
	v_mfma_f32_32x32x16_bf16 v[16:31], v[6:9], v[172:175], v[16:31]
	v_mfma_f32_32x32x16_bf16 v[64:79], v[80:83], v[172:175], v[64:79]
	s_waitcnt lgkmcnt(4)
	v_mfma_f32_32x32x16_bf16 v[48:63], v[10:13], v[172:175], v[48:63]
	v_cvt_pk_bf16_f32 v2, v189, v190
	v_cvt_pk_bf16_f32 v3, v191, v192
	v_cvt_pk_bf16_f32 v4, v193, v194
	v_cvt_pk_bf16_f32 v5, v195, v196
	s_waitcnt lgkmcnt(3)
	v_mfma_f32_32x32x16_bf16 v[32:47], v[84:87], v[2:5], v[32:47]
	s_waitcnt lgkmcnt(2)
	v_mfma_f32_32x32x16_bf16 v[16:31], v[88:91], v[2:5], v[16:31]
	s_waitcnt lgkmcnt(1)
	v_mfma_f32_32x32x16_bf16 v[64:79], v[168:171], v[2:5], v[64:79]
	s_waitcnt lgkmcnt(0)
	v_mfma_f32_32x32x16_bf16 v[48:63], v[92:95], v[2:5], v[48:63]
	v_mov_b32_e32 v158, v197
	s_andn2_b64 vcc, exec, s[16:17]
	s_cbranch_vccnz .LBB0_405
	s_branch .LBB0_404

; __device__ __forceinline__ unsigned cvt_pk_bf16(float lo, float hi) { unsigned r; asm volatile("v_cvt_pk_bf16_f32 %0, %1, %2" : "=v"(r) : "v"(lo), "v"(hi)); return r; }
; __device__ __forceinline__ float fast_exp2(float x) { return __builtin_amdgcn_exp2f(x); }
; template <int DQ, int TYPE>
; __device__ __forceinline__ void attn_item(PP p, int layer, int b, int h, int qt, char* lds, const int tid_, unsigned* next_ctr, volatile XLAS unsigned* slot) {
;     ...
;             float mx = fmaxf(sacc[0], sacc[1]);
; #pragma unroll
;             for (int i = 2; i < 16; i += 2) mx = fmaxf(mx, fmaxf(sacc[i], sacc[i + 1]));
;             mx *= c;
;             mx = fmaxf(mx, __shfl_xor(mx, 32));
;             const float m_old_ = m_run;
;             const float mnew = fmaxf(m_run, mx);
;             const float alpha = fast_exp2(m_run - mnew);
;             m_run = mnew;
;             float ls = 0.f;
; #pragma unroll
;             for (int i = 0; i < 16; ++i) { sacc[i] = fast_exp2(__builtin_fmaf(sacc[i], c, -mnew)); ls += sacc[i]; }
;             l_run = l_run * alpha + ls;
;             if (__builtin_amdgcn_ballot_w64(mx > m_old_) != 0) {
; #pragma unroll
;                 for (int md = 0; md < 4; ++md) O[md] *= alpha;
;             }
; #pragma unroll
;             for (int s2 = 0; s2 < 2; ++s2) {
;                 if (s2 == 0) {
; #pragma unroll
;                     for (int md = 0; md < 4; ++md) { vf[1][md][0] = *(const u32x2*)(vb0 + 16 + md * 32 * VLD); vf[1][md][1] = *(const u32x2*)(vb0 + 16 + md * 32 * VLD + 8); }
;                 }
;                 u32x4 pb;
;                 pb.x = cvt_pk_bf16(sacc[8 * s2 + 0], sacc[8 * s2 + 1]); pb.y = cvt_pk_bf16(sacc[8 * s2 + 2], sacc[8 * s2 + 3]);
;                 pb.z = cvt_pk_bf16(sacc[8 * s2 + 4], sacc[8 * s2 + 5]); pb.w = cvt_pk_bf16(sacc[8 * s2 + 6], sacc[8 * s2 + 7]);
;                 const bf16x8 bfrag = __builtin_bit_cast(bf16x8, pb);
;                 __builtin_amdgcn_sched_barrier(0);
; #pragma unroll
;                 for (int md = 0; md < 4; ++md) {
;                     u32x4 av; av.x = vf[s2][md][0].x; av.y = vf[s2][md][0].y; av.z = vf[s2][md][1].x; av.w = vf[s2][md][1].y;
;                     O[md] = __builtin_amdgcn_mfma_f32_32x32x16_bf16(__builtin_bit_cast(bf16x8, av), bfrag, O[md], 0, 0, 0);
;                 }
;                 __builtin_amdgcn_sched_barrier(0);
;             }
.LBB0_643:
	s_nop 10
	v_max3_f32 v152, v66, v67, v68
	v_max3_f32 v165, v69, v70, v71
	v_max3_f32 v177, v72, v73, v74
	v_max3_f32 v187, v75, v76, v77
	v_max3_f32 v152, v152, v78, v79
	v_max3_f32 v165, v165, v80, v81
	v_max3_f32 v152, v152, v177, v187
	v_max_f32_e32 v152, v152, v165
	v_mul_f32_e32 v152, 0x3e0293ee, v152
	v_mov_b32_e32 v165, v152
	s_nop 1
	v_permlane32_swap_b32_e32 v165, v152
	v_max_f32_e32 v177, v152, v165
	v_add_f32_e32 v152, 0x41000000, v176
	v_cmp_gt_f32_e32 vcc, v177, v152
	s_nop 1
	v_cndmask_b32_e32 v165, v176, v177, vcc
	v_sub_f32_e32 v152, v176, v165
	v_exp_f32_e32 v152, v152
	s_cbranch_vccz .LBB0_645
	v_pk_mul_f32 v[32:33], v[32:33], v[152:153] op_sel_hi:[1,0]
	v_pk_mul_f32 v[30:31], v[30:31], v[152:153] op_sel_hi:[1,0]
	v_pk_mul_f32 v[28:29], v[28:29], v[152:153] op_sel_hi:[1,0]
	v_pk_mul_f32 v[26:27], v[26:27], v[152:153] op_sel_hi:[1,0]
	v_pk_mul_f32 v[24:25], v[24:25], v[152:153] op_sel_hi:[1,0]
	v_pk_mul_f32 v[22:23], v[22:23], v[152:153] op_sel_hi:[1,0]
	v_pk_mul_f32 v[20:21], v[20:21], v[152:153] op_sel_hi:[1,0]
	v_pk_mul_f32 v[18:19], v[18:19], v[152:153] op_sel_hi:[1,0]
	v_pk_mul_f32 v[16:17], v[16:17], v[152:153] op_sel_hi:[1,0]
	v_pk_mul_f32 v[14:15], v[14:15], v[152:153] op_sel_hi:[1,0]
	v_pk_mul_f32 v[12:13], v[12:13], v[152:153] op_sel_hi:[1,0]
	v_pk_mul_f32 v[10:11], v[10:11], v[152:153] op_sel_hi:[1,0]
	v_pk_mul_f32 v[8:9], v[8:9], v[152:153] op_sel_hi:[1,0]
	v_pk_mul_f32 v[6:7], v[6:7], v[152:153] op_sel_hi:[1,0]
	v_pk_mul_f32 v[4:5], v[4:5], v[152:153] op_sel_hi:[1,0]
	v_pk_mul_f32 v[2:3], v[2:3], v[152:153] op_sel_hi:[1,0]
	v_pk_mul_f32 v[64:65], v[64:65], v[152:153] op_sel_hi:[1,0]
	v_pk_mul_f32 v[62:63], v[62:63], v[152:153] op_sel_hi:[1,0]
	v_pk_mul_f32 v[60:61], v[60:61], v[152:153] op_sel_hi:[1,0]
	v_pk_mul_f32 v[58:59], v[58:59], v[152:153] op_sel_hi:[1,0]
	v_pk_mul_f32 v[56:57], v[56:57], v[152:153] op_sel_hi:[1,0]
	v_pk_mul_f32 v[54:55], v[54:55], v[152:153] op_sel_hi:[1,0]
	v_pk_mul_f32 v[52:53], v[52:53], v[152:153] op_sel_hi:[1,0]
	v_pk_mul_f32 v[50:51], v[50:51], v[152:153] op_sel_hi:[1,0]
	v_pk_mul_f32 v[48:49], v[48:49], v[152:153] op_sel_hi:[1,0]
	v_pk_mul_f32 v[46:47], v[46:47], v[152:153] op_sel_hi:[1,0]
	v_pk_mul_f32 v[44:45], v[44:45], v[152:153] op_sel_hi:[1,0]
	v_pk_mul_f32 v[42:43], v[42:43], v[152:153] op_sel_hi:[1,0]
	v_pk_mul_f32 v[40:41], v[40:41], v[152:153] op_sel_hi:[1,0]
	v_pk_mul_f32 v[38:39], v[38:39], v[152:153] op_sel_hi:[1,0]
	v_pk_mul_f32 v[36:37], v[36:37], v[152:153] op_sel_hi:[1,0]
	v_pk_mul_f32 v[34:35], v[34:35], v[152:153] op_sel_hi:[1,0]
.LBB0_645:
	v_fma_f32 v66, v66, s33, -v165
	v_exp_f32_e32 v176, v66
	v_fma_f32 v66, v67, s33, -v165
	v_exp_f32_e32 v177, v66
	v_fma_f32 v66, v68, s33, -v165
	v_exp_f32_e32 v187, v66
	v_fma_f32 v66, v69, s33, -v165
	v_exp_f32_e32 v189, v66
	v_fma_f32 v67, v70, s33, -v165
	v_add_f32_e32 v66, 0, v176
	v_exp_f32_e32 v190, v67
	v_fma_f32 v67, v71, s33, -v165
	v_add_f32_e32 v66, v177, v66
	v_exp_f32_e32 v191, v67
	v_fma_f32 v67, v72, s33, -v165
	v_add_f32_e32 v66, v187, v66
	v_exp_f32_e32 v192, v67
	v_fma_f32 v67, v73, s33, -v165
	v_add_f32_e32 v66, v189, v66
	v_exp_f32_e32 v193, v67
	v_fma_f32 v67, v74, s33, -v165
	v_add_f32_e32 v66, v190, v66
	v_exp_f32_e32 v194, v67
	v_fma_f32 v67, v75, s33, -v165
	v_add_f32_e32 v66, v191, v66
	v_exp_f32_e32 v195, v67
	v_fma_f32 v67, v76, s33, -v165
	v_add_f32_e32 v66, v192, v66
	v_exp_f32_e32 v196, v67
	v_fma_f32 v67, v77, s33, -v165
	v_add_f32_e32 v66, v193, v66
	v_exp_f32_e32 v197, v67
	v_fma_f32 v67, v78, s33, -v165
	v_add_f32_e32 v66, v194, v66
	v_exp_f32_e32 v198, v67
	v_fma_f32 v67, v79, s33, -v165
	v_add_f32_e32 v66, v195, v66
	v_exp_f32_e32 v199, v67
	v_fma_f32 v67, v80, s33, -v165
	v_add_f32_e32 v66, v196, v66
	v_exp_f32_e32 v200, v67
	v_fma_f32 v67, v81, s33, -v165
	v_add_f32_e32 v66, v197, v66
	v_exp_f32_e32 v201, v67
	v_add_f32_e32 v66, v198, v66
	v_add_f32_e32 v66, v199, v66
	v_add_f32_e32 v66, v200, v66
	v_add_f32_e32 v202, v201, v66
	ds_read2_b64 v[66:69], v173 offset0:132 offset1:134
	ds_read2_b64 v[70:73], v175 offset0:164 offset1:166
	ds_read2_b64 v[74:77], v174 offset0:196 offset1:198
	ds_read2_b64 v[78:81], v172 offset0:228 offset1:230
	v_fmac_f32_e32 v202, v164, v152
	v_cvt_pk_bf16_f32 v172, v176, v177
	v_cvt_pk_bf16_f32 v173, v187, v189
	v_cvt_pk_bf16_f32 v174, v190, v191
	v_cvt_pk_bf16_f32 v175, v192, v193
	s_waitcnt lgkmcnt(4)
	s_nop 0
	v_mfma_f32_32x32x16_bf16 v[18:33], v[142:145], v[172:175], v[18:33]
	v_mfma_f32_32x32x16_bf16 v[2:17], v[138:141], v[172:175], v[2:17]
	v_mfma_f32_32x32x16_bf16 v[50:65], v[134:137], v[172:175], v[50:65]
	v_mfma_f32_32x32x16_bf16 v[34:49], v[130:133], v[172:175], v[34:49]
	v_cvt_pk_bf16_f32 v130, v194, v195
	v_cvt_pk_bf16_f32 v131, v196, v197
	v_cvt_pk_bf16_f32 v132, v198, v199
	v_cvt_pk_bf16_f32 v133, v200, v201
	s_waitcnt lgkmcnt(3)
	v_mfma_f32_32x32x16_bf16 v[18:33], v[66:69], v[130:133], v[18:33]
	s_waitcnt lgkmcnt(2)
	v_mfma_f32_32x32x16_bf16 v[2:17], v[70:73], v[130:133], v[2:17]
	s_waitcnt lgkmcnt(1)
	v_mfma_f32_32x32x16_bf16 v[50:65], v[74:77], v[130:133], v[50:65]
	s_waitcnt lgkmcnt(0)
	v_mfma_f32_32x32x16_bf16 v[34:49], v[78:81], v[130:133], v[34:49]
	v_mov_b32_e32 v164, v202
	s_andn2_b64 vcc, exec, s[12:13]
	s_cbranch_vccz .LBB0_647
	s_branch .LBB0_648

; __device__ __forceinline__ unsigned cvt_pk_bf16(float lo, float hi) { unsigned r; asm volatile("v_cvt_pk_bf16_f32 %0, %1, %2" : "=v"(r) : "v"(lo), "v"(hi)); return r; }
; __device__ __forceinline__ float fast_exp2(float x) { return __builtin_amdgcn_exp2f(x); }
; template <int DQ, int TYPE>
; __device__ __forceinline__ void attn_item(PP p, int layer, int b, int h, int qt, char* lds, const int tid_, unsigned* next_ctr, volatile XLAS unsigned* slot) {
;     ...
;             float mx = fmaxf(sacc[0], sacc[1]);
; #pragma unroll
;             for (int i = 2; i < 16; i += 2) mx = fmaxf(mx, fmaxf(sacc[i], sacc[i + 1]));
;             mx *= c;
;             mx = fmaxf(mx, __shfl_xor(mx, 32));
;             const float m_old_ = m_run;
;             const float mnew = fmaxf(m_run, mx);
;             const float alpha = fast_exp2(m_run - mnew);
;             m_run = mnew;
;             float ls = 0.f;
; #pragma unroll
;             for (int i = 0; i < 16; ++i) { sacc[i] = fast_exp2(__builtin_fmaf(sacc[i], c, -mnew)); ls += sacc[i]; }
;             l_run = l_run * alpha + ls;
;             if (__builtin_amdgcn_ballot_w64(mx > m_old_) != 0) {
; #pragma unroll
;                 for (int md = 0; md < 4; ++md) O[md] *= alpha;
;             }
; #pragma unroll
;             for (int s2 = 0; s2 < 2; ++s2) {
;                 if (s2 == 0) {
; #pragma unroll
;                     for (int md = 0; md < 4; ++md) { vf[1][md][0] = *(const u32x2*)(vb0 + 16 + md * 32 * VLD); vf[1][md][1] = *(const u32x2*)(vb0 + 16 + md * 32 * VLD + 8); }
;                 }
;                 u32x4 pb;
;                 pb.x = cvt_pk_bf16(sacc[8 * s2 + 0], sacc[8 * s2 + 1]); pb.y = cvt_pk_bf16(sacc[8 * s2 + 2], sacc[8 * s2 + 3]);
;                 pb.z = cvt_pk_bf16(sacc[8 * s2 + 4], sacc[8 * s2 + 5]); pb.w = cvt_pk_bf16(sacc[8 * s2 + 6], sacc[8 * s2 + 7]);
;                 const bf16x8 bfrag = __builtin_bit_cast(bf16x8, pb);
;                 __builtin_amdgcn_sched_barrier(0);
; #pragma unroll
;                 for (int md = 0; md < 4; ++md) {
;                     u32x4 av; av.x = vf[s2][md][0].x; av.y = vf[s2][md][0].y; av.z = vf[s2][md][1].x; av.w = vf[s2][md][1].y;
;                     O[md] = __builtin_amdgcn_mfma_f32_32x32x16_bf16(__builtin_bit_cast(bf16x8, av), bfrag, O[md], 0, 0, 0);
;                 }
;                 __builtin_amdgcn_sched_barrier(0);
;             }
.LBB0_667:
	s_nop 10
	v_max3_f32 v192, v66, v67, v68
	v_max3_f32 v200, v69, v70, v71
	v_max3_f32 v206, v72, v73, v74
	v_max3_f32 v207, v75, v76, v77
	v_max3_f32 v192, v192, v78, v79
	v_max3_f32 v200, v200, v80, v81
	v_max3_f32 v192, v192, v206, v207
	v_max_f32_e32 v192, v192, v200
	v_mul_f32_e32 v192, 0x3dd53b94, v192
	v_mov_b32_e32 v200, v192
	s_nop 1
	v_permlane32_swap_b32_e32 v200, v192
	v_max_f32_e32 v206, v192, v200
	v_add_f32_e32 v192, 0x41000000, v205
	v_cmp_gt_f32_e32 vcc, v206, v192
	s_nop 1
	v_cndmask_b32_e32 v200, v205, v206, vcc
	v_sub_f32_e32 v192, v205, v200
	v_exp_f32_e32 v192, v192
	s_cbranch_vccz .LBB0_669
	v_pk_mul_f32 v[32:33], v[32:33], v[192:193] op_sel_hi:[1,0]
	v_pk_mul_f32 v[30:31], v[30:31], v[192:193] op_sel_hi:[1,0]
	v_pk_mul_f32 v[28:29], v[28:29], v[192:193] op_sel_hi:[1,0]
	v_pk_mul_f32 v[26:27], v[26:27], v[192:193] op_sel_hi:[1,0]
	v_pk_mul_f32 v[24:25], v[24:25], v[192:193] op_sel_hi:[1,0]
	v_pk_mul_f32 v[22:23], v[22:23], v[192:193] op_sel_hi:[1,0]
	v_pk_mul_f32 v[20:21], v[20:21], v[192:193] op_sel_hi:[1,0]
	v_pk_mul_f32 v[18:19], v[18:19], v[192:193] op_sel_hi:[1,0]
	v_pk_mul_f32 v[16:17], v[16:17], v[192:193] op_sel_hi:[1,0]
	v_pk_mul_f32 v[14:15], v[14:15], v[192:193] op_sel_hi:[1,0]
	v_pk_mul_f32 v[12:13], v[12:13], v[192:193] op_sel_hi:[1,0]
	v_pk_mul_f32 v[10:11], v[10:11], v[192:193] op_sel_hi:[1,0]
	v_pk_mul_f32 v[8:9], v[8:9], v[192:193] op_sel_hi:[1,0]
	v_pk_mul_f32 v[6:7], v[6:7], v[192:193] op_sel_hi:[1,0]
	v_pk_mul_f32 v[4:5], v[4:5], v[192:193] op_sel_hi:[1,0]
	v_pk_mul_f32 v[2:3], v[2:3], v[192:193] op_sel_hi:[1,0]
	v_pk_mul_f32 v[64:65], v[64:65], v[192:193] op_sel_hi:[1,0]
	v_pk_mul_f32 v[62:63], v[62:63], v[192:193] op_sel_hi:[1,0]
	v_pk_mul_f32 v[60:61], v[60:61], v[192:193] op_sel_hi:[1,0]
	v_pk_mul_f32 v[58:59], v[58:59], v[192:193] op_sel_hi:[1,0]
	v_pk_mul_f32 v[56:57], v[56:57], v[192:193] op_sel_hi:[1,0]
	v_pk_mul_f32 v[54:55], v[54:55], v[192:193] op_sel_hi:[1,0]
	v_pk_mul_f32 v[52:53], v[52:53], v[192:193] op_sel_hi:[1,0]
	v_pk_mul_f32 v[50:51], v[50:51], v[192:193] op_sel_hi:[1,0]
	v_pk_mul_f32 v[48:49], v[48:49], v[192:193] op_sel_hi:[1,0]
	v_pk_mul_f32 v[46:47], v[46:47], v[192:193] op_sel_hi:[1,0]
	v_pk_mul_f32 v[44:45], v[44:45], v[192:193] op_sel_hi:[1,0]
	v_pk_mul_f32 v[42:43], v[42:43], v[192:193] op_sel_hi:[1,0]
	v_pk_mul_f32 v[40:41], v[40:41], v[192:193] op_sel_hi:[1,0]
	v_pk_mul_f32 v[38:39], v[38:39], v[192:193] op_sel_hi:[1,0]
	v_pk_mul_f32 v[36:37], v[36:37], v[192:193] op_sel_hi:[1,0]
	v_pk_mul_f32 v[34:35], v[34:35], v[192:193] op_sel_hi:[1,0]
.LBB0_669:
	v_fma_f32 v66, v66, s86, -v200
	v_exp_f32_e32 v205, v66
	v_fma_f32 v66, v67, s86, -v200
	v_exp_f32_e32 v206, v66
	v_fma_f32 v66, v68, s86, -v200
	v_exp_f32_e32 v207, v66
	v_fma_f32 v66, v69, s86, -v200
	v_exp_f32_e32 v208, v66
	v_fma_f32 v67, v70, s86, -v200
	v_add_f32_e32 v66, 0, v205
	v_exp_f32_e32 v209, v67
	v_fma_f32 v67, v71, s86, -v200
	v_add_f32_e32 v66, v206, v66
	v_exp_f32_e32 v210, v67
	v_fma_f32 v67, v72, s86, -v200
	v_add_f32_e32 v66, v207, v66
	v_exp_f32_e32 v211, v67
	v_fma_f32 v67, v73, s86, -v200
	v_add_f32_e32 v66, v208, v66
	v_exp_f32_e32 v212, v67
	v_fma_f32 v67, v74, s86, -v200
	v_add_f32_e32 v66, v209, v66
	v_exp_f32_e32 v213, v67
	v_fma_f32 v67, v75, s86, -v200
	v_add_f32_e32 v66, v210, v66
	v_exp_f32_e32 v214, v67
	v_fma_f32 v67, v76, s86, -v200
	v_add_f32_e32 v66, v211, v66
	v_exp_f32_e32 v215, v67
	v_fma_f32 v67, v77, s86, -v200
	v_add_f32_e32 v66, v212, v66
	v_exp_f32_e32 v216, v67
	v_fma_f32 v67, v78, s86, -v200
	v_add_f32_e32 v66, v213, v66
	v_exp_f32_e32 v217, v67
	v_fma_f32 v67, v79, s86, -v200
	v_add_f32_e32 v66, v214, v66
	v_exp_f32_e32 v218, v67
	v_fma_f32 v67, v80, s86, -v200
	v_add_f32_e32 v66, v215, v66
	v_exp_f32_e32 v219, v67
	v_fma_f32 v67, v81, s86, -v200
	v_add_f32_e32 v66, v216, v66
	v_exp_f32_e32 v230, v67
	v_add_f32_e32 v66, v217, v66
	v_add_f32_e32 v66, v218, v66
	v_add_f32_e32 v66, v219, v66
	v_add_f32_e32 v231, v230, v66
	ds_read2_b64 v[66:69], v203 offset0:132 offset1:134
	ds_read2_b64 v[70:73], v201 offset0:164 offset1:166
	ds_read2_b64 v[74:77], v204 offset0:196 offset1:198
	ds_read2_b64 v[78:81], v202 offset0:228 offset1:230
	v_fmac_f32_e32 v231, v199, v192
	v_cvt_pk_bf16_f32 v202, v205, v206
	v_cvt_pk_bf16_f32 v203, v207, v208
	v_cvt_pk_bf16_f32 v204, v209, v210
	v_cvt_pk_bf16_f32 v205, v211, v212
	s_waitcnt lgkmcnt(4)
	s_nop 0
	v_mfma_f32_32x32x16_bf16 v[18:33], v[162:165], v[202:205], v[18:33]
	v_mfma_f32_32x32x16_bf16 v[2:17], v[158:161], v[202:205], v[2:17]
	v_mfma_f32_32x32x16_bf16 v[50:65], v[154:157], v[202:205], v[50:65]
	v_mfma_f32_32x32x16_bf16 v[34:49], v[150:153], v[202:205], v[34:49]
	v_cvt_pk_bf16_f32 v150, v213, v214
	v_cvt_pk_bf16_f32 v151, v215, v216
	v_cvt_pk_bf16_f32 v152, v217, v218
	v_cvt_pk_bf16_f32 v153, v219, v230
	s_waitcnt lgkmcnt(3)
	v_mfma_f32_32x32x16_bf16 v[18:33], v[66:69], v[150:153], v[18:33]
	s_waitcnt lgkmcnt(2)
	v_mfma_f32_32x32x16_bf16 v[2:17], v[70:73], v[150:153], v[2:17]
	s_waitcnt lgkmcnt(1)
	v_mfma_f32_32x32x16_bf16 v[50:65], v[74:77], v[150:153], v[50:65]
	s_waitcnt lgkmcnt(0)
	v_mfma_f32_32x32x16_bf16 v[34:49], v[78:81], v[150:153], v[34:49]
	v_mov_b32_e32 v199, v231
	s_andn2_b64 vcc, exec, s[12:13]
	s_cbranch_vccz .LBB0_671
	s_branch .LBB0_672
